# attention: younger-half priority raise everywhere in the phase except inside the MFMA tile loop (dropped at the loop header, raised again behind the loop)
# speedup vs baseline: 1.0006x; 1.0006x over previous
; __global__ void __launch_bounds__(NWAVES * 64, 2) hymba_fwd(Args args) {
;     ...
;         const float lam = ((const float*)ctl)[CW_LAM];
;         constexpr int NU = 512 + 1024;
;         for (;;) {
;             if (tid == 0) MISC[0] = atomicAdd(ctl + CW_QCTR, 1u);
.LBB0_290:
	v_mov_b32_e32 v177, 0
	s_barrier
	v_readfirstlane_b32 s101, v210
	s_lshr_b32 s101, s101, 8
	s_cmp_lg_u32 s101, 0
	s_cbranch_scc0 .Lattn_po0
	s_setprio 1

; #define SBAR() __builtin_amdgcn_sched_barrier(0)
; #define SLOADB(k0) do { vsB0 = *(const bf16x8*)(&Vh[(size_t)((k0) + sr) * LDP + sc]); vsB1 = *(const bf16x8*)(&Vh[(size_t)((k0) + 32 + sr) * LDP + sc]); \
;     ksB0 = *(const bf16x8*)(&Kh[(size_t)((k0) + sr) * LDP + sc]); ksB1 = *(const bf16x8*)(&Kh[(size_t)((k0) + 32 + sr) * LDP + sc]); } while (0)
; __device__ __forceinline__ void sc_init(f32x16& p0, f32x16& p1, float dq, float nsl2, float m_ref, int side) {
;   if (side != 0) { const float sg = (float)side; const float base0 = fmaf(sg * nsl2, dq, -m_ref), base1 = base0 - sg * 32.f * nsl2;
; #pragma unroll
;     for (int r = 0; r < 16; ++r) { const float c = -sg * nsl2 * (float)((r & 3) + 8 * (r >> 2)); p0[r] = base0 + c; p1[r] = base1 + c; }
;   } else {
; #pragma unroll
;     for (int r = 0; r < 16; ++r) { const float kv = (float)((r & 3) + 8 * (r >> 2)); const float d0 = dq - kv, d1 = d0 - 32.f;
;       p0[r] = fmaf(nsl2, __builtin_fabsf(d0), -m_ref); p1[r] = fmaf(nsl2, __builtin_fabsf(d1), -m_ref); }
;   }
; }
; __device__ __forceinline__ void attn_unit(const bf16* __restrict__ P, bf16* __restrict__ MIXIN, const float* __restrict__ gn, int seq0, int h, int q0, int nt, float kmax0, float kmax1, float slope, float lam, char* lds) {
;     ...
;   for (int j = t0 + 1; j + 1 < t1; j += 2) {
;     if (j + 2 < t1) SLOADB((j + 2) * 64); SBAR();
;     sc_init(pB0, pB1, DQ(j), nsl2, m_reg, SIDE(j)); SBAR();
.LBB0_323:
	s_setprio 0
	s_add_i32 s6, s33, -1
	s_cmp_gt_u32 s6, s73
	v_cvt_f32_i32_e32 v97, s6
	s_cselect_b64 s[0:1], -1, 0
	s_cmp_ge_u32 s6, s72
	v_cndmask_b32_e64 v96, 0, -1, s[0:1]
	s_cselect_b64 vcc, -1, 0
	v_cndmask_b32_e32 v96, 1, v96, vcc
	v_cmp_ne_u32_e32 vcc, 0, v96
	v_fmamk_f32 v208, v97, 0xc2800000, v184
	s_cbranch_vccz .LBB0_333
	v_cvt_f32_i32_e32 v96, v96
	v_mul_f32_e32 v98, v180, v96
	v_mul_f32_e32 v97, 0x42000000, v96
	v_xor_b32_e32 v96, 0x80000000, v96
	v_fma_f32 v179, v98, v208, -v182
	v_pk_mul_f32 v[214:215], v[188:189], v[96:97]
	v_pk_fma_f32 v[216:217], v[188:189], v[96:97], v[178:179] neg_lo:[1,0,0] neg_hi:[1,0,0]
	v_mul_f32_e32 v112, 0, v214
	v_pk_mul_f32 v[114:115], v[214:215], s[14:15]
	v_mov_b32_e32 v113, v214
	v_pk_add_f32 v[96:97], v[112:113], v[216:217] op_sel:[0,1]
	v_pk_fma_f32 v[98:99], v[214:215], s[48:49], v[216:217] op_sel:[0,0,1] op_sel_hi:[0,1,1]
	v_pk_fma_f32 v[100:101], v[214:215], s[50:51], v[216:217] op_sel:[0,0,1] op_sel_hi:[0,1,1]
	v_pk_fma_f32 v[102:103], v[214:215], s[58:59], v[216:217] op_sel:[0,0,1] op_sel_hi:[0,1,1]
	v_pk_fma_f32 v[104:105], v[214:215], s[64:65], v[216:217] op_sel:[0,0,1] op_sel_hi:[0,1,1]
	v_pk_fma_f32 v[106:107], v[214:215], s[80:81], v[216:217] op_sel:[0,0,1] op_sel_hi:[0,1,1]
	v_pk_fma_f32 v[108:109], v[214:215], s[82:83], v[216:217] op_sel:[0,0,1] op_sel_hi:[0,1,1]
	v_pk_fma_f32 v[110:111], v[214:215], s[14:15], v[216:217] op_sel:[0,0,1] op_sel_hi:[1,1,0]
	v_mul_f32_e32 v115, 0x41d80000, v214
	v_mov_b32_e32 v216, v179
	v_pk_add_f32 v[126:127], v[216:217], v[114:115] op_sel_hi:[0,1]
	v_pk_add_f32 v[112:113], v[216:217], v[112:113] op_sel_hi:[0,1]
	v_pk_fma_f32 v[124:125], v[214:215], s[82:83], v[216:217] op_sel_hi:[0,1,0]
	v_pk_fma_f32 v[122:123], v[214:215], s[80:81], v[216:217] op_sel_hi:[0,1,0]
	v_pk_fma_f32 v[120:121], v[214:215], s[64:65], v[216:217] op_sel_hi:[0,1,0]
	v_pk_fma_f32 v[118:119], v[214:215], s[58:59], v[216:217] op_sel_hi:[0,1,0]
	v_pk_fma_f32 v[116:117], v[214:215], s[50:51], v[216:217] op_sel_hi:[0,1,0]
	v_pk_fma_f32 v[114:115], v[214:215], s[48:49], v[216:217] op_sel_hi:[0,1,0]
	v_fmac_f32_e32 v217, 0x41d80000, v214
	v_mov_b32_e32 v111, v217
	s_cbranch_execnz .LBB0_326

; #define SBAR() __builtin_amdgcn_sched_barrier(0)
; __device__ __forceinline__ void sc_init(f32x16& p0, f32x16& p1, float dq, float nsl2, float m_ref, int side) {
;   if (side != 0) { const float sg = (float)side; const float base0 = fmaf(sg * nsl2, dq, -m_ref), base1 = base0 - sg * 32.f * nsl2;
; #pragma unroll
;     for (int r = 0; r < 16; ++r) { const float c = -sg * nsl2 * (float)((r & 3) + 8 * (r >> 2)); p0[r] = base0 + c; p1[r] = base1 + c; }
;   } else {
; #pragma unroll
;     for (int r = 0; r < 16; ++r) { const float kv = (float)((r & 3) + 8 * (r >> 2)); const float d0 = dq - kv, d1 = d0 - 32.f;
;       p0[r] = fmaf(nsl2, __builtin_fabsf(d0), -m_ref); p1[r] = fmaf(nsl2, __builtin_fabsf(d1), -m_ref); }
;   }
; }
; __device__ __forceinline__ void attn_unit(const bf16* __restrict__ P, bf16* __restrict__ MIXIN, const float* __restrict__ gn, int seq0, int h, int q0, int nt, float kmax0, float kmax1, float slope, float lam, char* lds) {
;     ...
;   }
;   sc_init(pB0, pB1, DQ(t1 - 1), nsl2, m_reg, SIDE(t1 - 1)); SBAR();
.Lattn_q1:
	s_or_b64 exec, exec, s[98:99]
	s_cmp_lg_u32 s101, 0
	s_cbranch_scc0 .Lattn_po1
	s_setprio 1
.Lattn_po1:
	s_nop 0
	s_lshl_b32 s24, s85, 7
	s_add_i32 s0, s3, -1
	v_cvt_f32_i32_e32 v96, s0
	s_cmp_gt_i32 s0, s73
	s_cselect_b64 s[0:1], -1, 0
	s_cmp_gt_i32 s3, s72
	v_fmac_f32_e32 v184, 0xc2800000, v96
	v_cndmask_b32_e64 v96, 0, -1, s[0:1]
	s_cselect_b64 vcc, -1, 0
	v_cndmask_b32_e32 v96, 1, v96, vcc
	v_cmp_ne_u32_e32 vcc, 0, v96
	s_cbranch_vccz .LBB0_347
	v_cvt_f32_i32_e32 v96, v96
	v_mul_f32_e32 v98, v180, v96
	v_mul_f32_e32 v97, 0x42000000, v96
	v_xor_b32_e32 v96, 0x80000000, v96
	v_fma_f32 v179, v98, v184, -v182
	v_pk_mul_f32 v[144:145], v[180:181], v[96:97] op_sel_hi:[0,1]
	v_mul_f32_e32 v112, 0, v144
	v_pk_mul_f32 v[114:115], v[144:145], s[14:15]
	v_pk_fma_f32 v[146:147], v[180:181], v[96:97], v[178:179] op_sel_hi:[0,1,1] neg_lo:[1,0,0] neg_hi:[1,0,0]
	v_mov_b32_e32 v113, v144
	v_pk_add_f32 v[96:97], v[112:113], v[146:147] op_sel:[0,1]
	v_pk_fma_f32 v[98:99], v[144:145], s[48:49], v[146:147] op_sel:[0,0,1] op_sel_hi:[0,1,1]
	v_pk_fma_f32 v[100:101], v[144:145], s[50:51], v[146:147] op_sel:[0,0,1] op_sel_hi:[0,1,1]
	v_pk_fma_f32 v[102:103], v[144:145], s[58:59], v[146:147] op_sel:[0,0,1] op_sel_hi:[0,1,1]
	v_pk_fma_f32 v[104:105], v[144:145], s[64:65], v[146:147] op_sel:[0,0,1] op_sel_hi:[0,1,1]
	v_pk_fma_f32 v[106:107], v[144:145], s[80:81], v[146:147] op_sel:[0,0,1] op_sel_hi:[0,1,1]
	v_pk_fma_f32 v[108:109], v[144:145], s[82:83], v[146:147] op_sel:[0,0,1] op_sel_hi:[0,1,1]
	v_pk_fma_f32 v[110:111], v[144:145], s[14:15], v[146:147] op_sel:[0,0,1] op_sel_hi:[1,1,0]
	v_mul_f32_e32 v115, 0x41d80000, v144
	v_mov_b32_e32 v146, v179
	v_pk_add_f32 v[126:127], v[146:147], v[114:115] op_sel_hi:[0,1]
	v_pk_add_f32 v[112:113], v[146:147], v[112:113] op_sel_hi:[0,1]
	v_pk_fma_f32 v[124:125], v[144:145], s[82:83], v[146:147] op_sel_hi:[0,1,0]
	v_pk_fma_f32 v[122:123], v[144:145], s[80:81], v[146:147] op_sel_hi:[0,1,0]
	v_pk_fma_f32 v[120:121], v[144:145], s[64:65], v[146:147] op_sel_hi:[0,1,0]
	v_pk_fma_f32 v[118:119], v[144:145], s[58:59], v[146:147] op_sel_hi:[0,1,0]
	v_pk_fma_f32 v[116:117], v[144:145], s[50:51], v[146:147] op_sel_hi:[0,1,0]
	v_pk_fma_f32 v[114:115], v[144:145], s[48:49], v[146:147] op_sel_hi:[0,1,0]
	v_fmac_f32_e32 v147, 0x41d80000, v144
	v_mov_b32_e32 v111, v147
	s_cbranch_execnz .LBB0_340
